# stick-breaking K/V tiles staged through per-wave double-buffered LDS with coalesced LDS-DMA loads (8 per tile) instead of 32-row register gathers, on top of the rewritten tile math
# speedup vs baseline: 1.0051x; 1.0041x over previous
; __device__ __forceinline__ int otid() { int t = threadIdx.x; asm volatile("" : "+v"(t)); return t; }
; __device__ __forceinline__ void sb_load(SbFrags& F, const bf16_t* Pm, const bf16_t* VT, size_t tok0, int kv0, int h, int r32, int hi) {
;     const bf16_t* krow = Pm + (tok0 + kv0 + r32) * PW + PC_SBK + h * 64;
; #pragma unroll
;     for (int s = 0; s < 4; ++s) F.kf[s] = *(const bf16x8*)(krow + 16 * s + 8 * hi);
; #pragma unroll
;     for (int s = 0; s < 2; ++s) {
;         const bf16_t* v0p = VT + (size_t)(h * 64 + r32) * VTLD + tok0 + kv0 + 16 * s + 4 * hi; const bf16_t* v1p = v0p + (size_t)32 * VTLD;
;         F.v[4 * s + 0] = *(const s16x4*)v0p; F.v[4 * s + 1] = *(const s16x4*)(v0p + 8); F.v[4 * s + 2] = *(const s16x4*)v1p; F.v[4 * s + 3] = *(const s16x4*)(v1p + 8);
;     }
; }
; template <bool DRY> __device__ __forceinline__ void sb_unit(int b, int h, int qi, bf16_t* Pm, const bf16_t* VT) {
;     const int lane = otid() & 63, r32 = lane & 31, hi = lane >> 5;
;     const size_t tok0 = (size_t)b * SEQ; const int q0 = qi * 32;
;     bf16_t* qrow = Pm + (tok0 + q0 + r32) * PW + PC_SBQ + h * 64;
;     bf16x8 qf[4];
; #pragma unroll
;     for (int s = 0; s < 4; ++s) qf[s] = *(const bf16x8*)(qrow + 16 * s + 8 * hi);
;     float R = 0.f; f32x16 o0 = {}, o1 = {};
;     SbFrags cur, nxt;
;     sb_load(cur, Pm, VT, tok0, qi * 32, h, r32, hi);
; #pragma unroll 1
;     ...
;         sb_load(nxt, Pm, VT, tok0, (kt > 0 ? kt - 1 : 0) * 32, h, r32, hi);
.LBB0_741:
	v_ashrrev_i32_e32 v4, 9, v3
	v_mov_b32_e32 v0, v234
	s_waitcnt vmcnt(0)
	v_and_b32_e32 v100, 63, v3
	v_ashrrev_i32_e32 v5, 31, v4
	v_and_b32_e32 v15, 31, v0
	v_bfe_u32 v16, v0, 5, 1
	v_lshlrev_b64 v[0:1], 11, v[4:5]
	v_lshlrev_b32_e32 v17, 5, v100
	v_or3_b32 v8, v15, v17, v0
	v_mov_b64_e32 v[6:7], s[42:43]
	v_and_b32_e32 v14, 0x1c0, v3
	v_mad_u64_u32 v[6:7], s[4:5], v8, s24, v[6:7]
	v_mad_i32_i24 v7, v1, s24, v7
	v_lshlrev_b32_e32 v8, 1, v14
	v_mov_b32_e32 v9, v2
	v_lshl_add_u64 v[84:85], v[6:7], 0, v[8:9]
	v_lshlrev_b32_e32 v10, 4, v16
	v_mov_b32_e32 v11, v2
	v_lshl_add_u64 v[12:13], v[84:85], 0, v[10:11]
	global_load_dwordx4 v[52:55], v[12:13], off offset:1280
	global_load_dwordx4 v[56:59], v[12:13], off offset:1312
	global_load_dwordx4 v[60:63], v[12:13], off offset:1344
	global_load_dwordx4 v[64:67], v[12:13], off offset:1376
	v_or_b32_e32 v12, v15, v14
	v_mul_u32_u24_e32 v12, 0x8200, v12
	v_lshlrev_b32_e32 v12, 1, v12
	v_mov_b32_e32 v13, v2
	v_lshl_add_u64 v[12:13], s[38:39], 0, v[12:13]
	v_lshlrev_b64 v[4:5], 12, v[4:5]
	v_lshlrev_b32_e32 v6, 3, v16
	v_mov_b32_e32 v7, v2
	v_lshl_add_u64 v[4:5], v[12:13], 0, v[4:5]
	v_lshlrev_b32_e32 v12, 6, v100
	v_mov_b32_e32 v13, v2
	v_lshl_add_u64 v[12:13], v[4:5], 0, v[12:13]
	v_lshl_add_u64 v[88:89], v[4:5], 0, v[6:7]
	v_xor_b32_e32 v4, 32, v238
	v_add_u32_e32 v5, 64, v239
	v_cmp_lt_i32_e32 vcc, v4, v5
	v_lshlrev_b32_e32 v86, 2, v16
	v_and_b32_e32 v98, 63, v87
	v_cndmask_b32_e32 v4, v238, v4, vcc
	v_lshlrev_b32_e32 v101, 2, v4
	v_or_b32_e32 v4, 1, v86
	v_cmp_lt_u32_e64 s[46:47], v4, v15
	v_or_b32_e32 v4, 2, v86
	v_cmp_lt_u32_e64 s[48:49], v4, v15
	v_or_b32_e32 v4, 3, v86
	v_cmp_lt_u32_e64 s[50:51], v4, v15
	v_or_b32_e32 v4, 8, v86
	v_cmp_lt_u32_e64 s[52:53], v4, v15
	v_or_b32_e32 v4, 9, v86
	v_cmp_lt_u32_e64 s[54:55], v4, v15
	v_or_b32_e32 v4, 10, v86
	v_cmp_lt_u32_e64 s[56:57], v4, v15
	v_or_b32_e32 v4, 11, v86
	v_cmp_lt_u32_e64 s[58:59], v4, v15
	v_or_b32_e32 v4, 16, v86
	v_cmp_lt_u32_e64 s[60:61], v4, v15
	v_or_b32_e32 v4, 17, v86
	v_cmp_lt_u32_e64 s[62:63], v4, v15
	v_or_b32_e32 v4, 18, v86
	v_cmp_lt_u32_e64 s[64:65], v4, v15
	v_or_b32_e32 v4, 19, v86
	v_cmp_lt_u32_e64 s[66:67], v4, v15
	v_or_b32_e32 v4, 24, v86
	v_cmp_lt_u32_e64 s[68:69], v4, v15
	v_or_b32_e32 v4, 25, v86
	v_cmp_lt_u32_e64 s[70:71], v4, v15
	v_or_b32_e32 v4, 26, v86
	v_cmp_lt_u32_e64 s[72:73], v4, v15
	v_or_b32_e32 v4, 27, v86
	v_or_b32_e32 v0, v0, v15
	v_cmp_lt_u32_e64 s[74:75], v4, v15
	v_lshl_add_u64 v[4:5], s[42:43], 0, v[8:9]
	v_mov_b32_e32 v102, 0
	v_lshlrev_b32_e32 v99, 5, v98
	v_or_b32_e32 v90, v0, v17
	v_mov_b32_e32 v91, v1
	v_lshl_add_u64 v[94:95], v[12:13], 0, v[6:7]
	s_mov_b32 s28, 0
	v_cmp_eq_u32_e64 s[12:13], 0, v16
	v_cmp_lt_u32_e64 s[44:45], v86, v15
	v_lshl_add_u64 v[92:93], v[4:5], 0, v[10:11]
	s_mov_b64 s[34:35], 0
	v_mov_b32_e32 v4, 0
	v_mov_b32_e32 v5, v102
	v_mov_b32_e32 v6, v102
	v_mov_b32_e32 v7, v102
	v_mov_b32_e32 v8, v102
	v_mov_b32_e32 v9, v102
	v_mov_b32_e32 v10, v102
	v_mov_b32_e32 v11, v102
	v_mov_b32_e32 v12, v102
	v_mov_b32_e32 v13, v102
	v_mov_b32_e32 v14, v102
	v_mov_b32_e32 v15, v102
	v_mov_b32_e32 v16, v102
	v_mov_b32_e32 v17, v102
	v_mov_b32_e32 v18, v102
	v_mov_b32_e32 v19, v102
	v_mov_b32_e32 v20, 0
	v_mov_b32_e32 v21, v102
	v_mov_b32_e32 v22, v102
	v_mov_b32_e32 v23, v102
	v_mov_b32_e32 v24, v102
	v_mov_b32_e32 v25, v102
	v_mov_b32_e32 v26, v102
	v_mov_b32_e32 v27, v102
	v_mov_b32_e32 v28, v102
	v_mov_b32_e32 v29, v102
	v_mov_b32_e32 v30, v102
	v_mov_b32_e32 v31, v102
	v_mov_b32_e32 v32, v102
	v_mov_b32_e32 v33, v102
	v_mov_b32_e32 v34, v102
	v_mov_b32_e32 v35, v102
	v_readfirstlane_b32 s14, v234
	s_lshl_b32 s98, s14, 8
	v_and_b32_e32 v36, 63, v234
	v_lshrrev_b32_e32 v37, 3, v36
	v_and_b32_e32 v38, 7, v36
	v_xor_b32_e32 v38, v38, v37
	v_ashrrev_i32_e32 v40, 9, v3
	v_lshlrev_b32_e32 v40, 11, v40
	v_and_b32_e32 v41, 63, v3
	v_lshl_add_u32 v40, v41, 5, v40
	v_bfe_u32 v42, v3, 6, 3
	v_add_u32_e32 v39, v40, v37
	v_lshlrev_b32_e32 v44, 7, v42
	v_lshl_add_u32 v44, v38, 4, v44
	v_add_u32_e32 v44, 0x900, v44
	v_mov_b32_e32 v45, 0
	v_mov_b64_e32 v[172:173], s[42:43]
	v_mad_u64_u32 v[172:173], vcc, v39, s24, v[172:173]
	v_lshl_add_u64 v[172:173], v[172:173], 0, v[44:45]
	v_mov_b32_e32 v46, 0xea00
	v_mov_b32_e32 v47, 0
	v_lshl_add_u64 v[174:175], v[172:173], 0, v[46:47]
	v_lshl_add_u64 v[176:177], v[174:175], 0, v[46:47]
	v_lshl_add_u64 v[178:179], v[176:177], 0, v[46:47]
	v_lshrrev_b32_e32 v37, 2, v36
	v_and_b32_e32 v38, 3, v36
	v_bfe_u32 v49, v36, 4, 2
	v_xor_b32_e32 v38, v38, v49
	v_lshl_add_u32 v39, v42, 6, v37
	v_lshlrev_b32_e32 v44, 1, v40
	v_lshl_add_u32 v44, v38, 4, v44
	v_mov_b64_e32 v[180:181], s[38:39]
	v_mov_b32_e32 v49, 0x10400
	v_mad_u64_u32 v[180:181], vcc, v39, v49, v[180:181]
	v_lshl_add_u64 v[180:181], v[180:181], 0, v[44:45]
	v_mov_b32_e32 v46, 0x104000
	v_lshl_add_u64 v[182:183], v[180:181], 0, v[46:47]
	v_lshl_add_u64 v[184:185], v[182:183], 0, v[46:47]
	v_lshl_add_u64 v[186:187], v[184:185], 0, v[46:47]
	v_mov_b32_e32 v188, 0xfffc5800
	v_mov_b32_e32 v189, -1
	v_mov_b32_e32 v190, 0xffffffc0
	v_mov_b32_e32 v191, -1
	v_and_b32_e32 v37, 31, v234
	v_bfe_u32 v38, v234, 5, 1
	v_and_b32_e32 v39, 7, v37
	v_lshlrev_b32_e32 v44, 7, v37
	v_add_u32_e32 v49, 0, v38
	v_xor_b32_e32 v49, v49, v39
	v_lshl_add_u32 v192, v49, 4, v44
	v_add_u32_e32 v49, 2, v38
	v_xor_b32_e32 v49, v49, v39
	v_lshl_add_u32 v193, v49, 4, v44
	v_add_u32_e32 v49, 4, v38
	v_xor_b32_e32 v49, v49, v39
	v_lshl_add_u32 v194, v49, 4, v44
	v_add_u32_e32 v49, 6, v38
	v_xor_b32_e32 v49, v49, v39
	v_lshl_add_u32 v195, v49, 4, v44
	v_bfe_u32 v39, v37, 2, 2
	v_lshlrev_b32_e32 v44, 6, v37
	v_lshl_add_u32 v44, v38, 3, v44
	v_xor_b32_e32 v49, 0, v39
	v_lshl_add_u32 v196, v49, 4, v44
	v_xor_b32_e32 v49, 1, v39
	v_lshl_add_u32 v197, v49, 4, v44
	v_xor_b32_e32 v49, 2, v39
	v_lshl_add_u32 v198, v49, 4, v44
	v_xor_b32_e32 v49, 3, v39
	v_lshl_add_u32 v199, v49, 4, v44
	s_add_i32 m0, s98, 0
	s_nop 0
	global_load_lds_dwordx4 v[172:173], off
	s_add_i32 m0, s98, 1024
	s_nop 0
	global_load_lds_dwordx4 v[174:175], off
	s_add_i32 m0, s98, 2048
	s_nop 0
	global_load_lds_dwordx4 v[176:177], off
	s_add_i32 m0, s98, 3072
	s_nop 0
	global_load_lds_dwordx4 v[178:179], off
	s_add_i32 m0, s98, 4096
	s_nop 0
	global_load_lds_dwordx4 v[180:181], off
	s_add_i32 m0, s98, 5120
	s_nop 0
	global_load_lds_dwordx4 v[182:183], off
	s_add_i32 m0, s98, 6144
	s_nop 0
	global_load_lds_dwordx4 v[184:185], off
	s_add_i32 m0, s98, 7168
	s_nop 0
	global_load_lds_dwordx4 v[186:187], off
	v_cmp_lt_i32_e32 vcc, 0, v100
	v_add_u32_e32 v100, -1, v100
	s_nop 0
	s_cbranch_vccz .Lsb_nostep_a
	v_lshl_add_u64 v[172:173], v[172:173], 0, v[188:189]
	v_lshl_add_u64 v[174:175], v[174:175], 0, v[188:189]
	v_lshl_add_u64 v[176:177], v[176:177], 0, v[188:189]
	v_lshl_add_u64 v[178:179], v[178:179], 0, v[188:189]
	v_lshl_add_u64 v[180:181], v[180:181], 0, v[190:191]
	v_lshl_add_u64 v[182:183], v[182:183], 0, v[190:191]
	v_lshl_add_u64 v[184:185], v[184:185], 0, v[190:191]
	v_lshl_add_u64 v[186:187], v[186:187], 0, v[190:191]
; __device__ __forceinline__ int crow(int r, int hi) { return (r & 3) + 8 * (r >> 2) + 4 * hi; }
; __device__ __forceinline__ void sb_load(SbFrags& F, const bf16_t* Pm, const bf16_t* VT, size_t tok0, int kv0, int h, int r32, int hi) {
;     const bf16_t* krow = Pm + (tok0 + kv0 + r32) * PW + PC_SBK + h * 64;
; #pragma unroll
;     for (int s = 0; s < 4; ++s) F.kf[s] = *(const bf16x8*)(krow + 16 * s + 8 * hi);
; #pragma unroll
;     for (int s = 0; s < 2; ++s) {
;         const bf16_t* v0p = VT + (size_t)(h * 64 + r32) * VTLD + tok0 + kv0 + 16 * s + 4 * hi; const bf16_t* v1p = v0p + (size_t)32 * VTLD;
;         F.v[4 * s + 0] = *(const s16x4*)v0p; F.v[4 * s + 1] = *(const s16x4*)(v0p + 8); F.v[4 * s + 2] = *(const s16x4*)v1p; F.v[4 * s + 3] = *(const s16x4*)(v1p + 8);
;     }
; template <bool DRY> __device__ __forceinline__ void sb_unit(int b, int h, int qi, bf16_t* Pm, const bf16_t* VT) {
;     ...
;         sb_load(nxt, Pm, VT, tok0, (kt > 0 ? kt - 1 : 0) * 32, h, r32, hi);
;         f32x16 p = {};
; #pragma unroll
;         for (int s = 0; s < 4; ++s) p = __builtin_amdgcn_mfma_f32_32x32x16_bf16(cur.kf[s], qf[s], p, 0, 0, 0);
;         const bool diag = (kt == qi);
;         float lk[16], inner[16], Tg[4], TP[4], pre[4];
; #pragma unroll
;         for (int r = 0; r < 16; ++r) {
;             const float z = p[r] * 0.125f; p[r] = z;
;             const float e = __expf(-fabsf(z)); const float sp = fmaxf(z, 0.f) + __logf(1.f + e);
;             const bool valid = !diag || (crow(r, hi) < r32);
;             lk[r] = valid ? -sp : 0.f;
;         }
.Lsb_nostep_a:
.LBB0_742:
	s_xor_b32 s98, s98, 0x2000
	s_add_i32 m0, s98, 0
	s_nop 0
	global_load_lds_dwordx4 v[172:173], off
	s_add_i32 m0, s98, 1024
	s_nop 0
	global_load_lds_dwordx4 v[174:175], off
	s_add_i32 m0, s98, 2048
	s_nop 0
	global_load_lds_dwordx4 v[176:177], off
	s_add_i32 m0, s98, 3072
	s_nop 0
	global_load_lds_dwordx4 v[178:179], off
	s_add_i32 m0, s98, 4096
	s_nop 0
	global_load_lds_dwordx4 v[180:181], off
	s_add_i32 m0, s98, 5120
	s_nop 0
	global_load_lds_dwordx4 v[182:183], off
	s_add_i32 m0, s98, 6144
	s_nop 0
	global_load_lds_dwordx4 v[184:185], off
	s_add_i32 m0, s98, 7168
	s_nop 0
	global_load_lds_dwordx4 v[186:187], off
	v_cmp_lt_i32_e32 vcc, 0, v100
	v_add_u32_e32 v100, -1, v100
	s_nop 0
	s_cbranch_vccz .Lsb_nostep_b
	v_lshl_add_u64 v[172:173], v[172:173], 0, v[188:189]
	v_lshl_add_u64 v[174:175], v[174:175], 0, v[188:189]
	v_lshl_add_u64 v[176:177], v[176:177], 0, v[188:189]
	v_lshl_add_u64 v[178:179], v[178:179], 0, v[188:189]
	v_lshl_add_u64 v[180:181], v[180:181], 0, v[190:191]
	v_lshl_add_u64 v[182:183], v[182:183], 0, v[190:191]
	v_lshl_add_u64 v[184:185], v[184:185], 0, v[190:191]
	v_lshl_add_u64 v[186:187], v[186:187], 0, v[190:191]
.Lsb_nostep_b:
	s_xor_b32 s99, s98, 0x2000
	v_add_u32_e32 v210, s99, v192
	v_add_u32_e32 v211, s99, v193
	v_add_u32_e32 v212, s99, v194
	v_add_u32_e32 v213, s99, v195
	v_add_u32_e32 v214, s99, v196
	v_add_u32_e32 v215, s99, v197
	v_add_u32_e32 v216, s99, v198
	v_add_u32_e32 v217, s99, v199
	s_waitcnt vmcnt(8)
	ds_read_b128 v[136:139], v210
	ds_read_b128 v[112:115], v211
	ds_read_b128 v[108:111], v212
	ds_read_b128 v[104:107], v213
	ds_read_b64 v[80:81], v214 offset:4096
	ds_read_b64 v[82:83], v215 offset:4096
	ds_read_b64 v[72:73], v216 offset:4096
	ds_read_b64 v[74:75], v217 offset:4096
	ds_read_b64 v[76:77], v214 offset:6144
	ds_read_b64 v[78:79], v215 offset:6144
	ds_read_b64 v[68:69], v216 offset:6144
	ds_read_b64 v[70:71], v217 offset:6144
	s_waitcnt lgkmcnt(8)
	v_mfma_f32_32x32x16_bf16 v[36:51], v[136:139], v[52:55], 0
	v_mfma_f32_32x32x16_bf16 v[36:51], v[112:115], v[56:59], v[36:51]
	v_mfma_f32_32x32x16_bf16 v[36:51], v[108:111], v[60:63], v[36:51]
	v_mfma_f32_32x32x16_bf16 v[36:51], v[104:107], v[64:67], v[36:51]
	s_nop 11
	v_mul_f32_e32 v36, 0x3e38aa3b, v36
	v_mul_f32_e32 v37, 0x3e38aa3b, v37
	v_exp_f32_e64 v96, -|v36|
	v_exp_f32_e64 v97, -|v37|
	v_min_f32_e64 v104, -v36, 0
	v_min_f32_e64 v105, -v37, 0
	v_add_f32_e32 v96, 1.0, v96
	v_add_f32_e32 v97, 1.0, v97
	v_log_f32_e32 v96, v96
	v_log_f32_e32 v97, v97
	v_cndmask_b32_e64 v121, v102, 0, s[12:13]
	v_sub_f32_e32 v104, v104, v96
	v_sub_f32_e32 v105, v105, v97
	v_cndmask_b32_e64 v104, 0, v104, s[44:45]
	v_cndmask_b32_e64 v105, 0, v105, s[46:47]
	v_mul_f32_e32 v38, 0x3e38aa3b, v38
	v_mul_f32_e32 v39, 0x3e38aa3b, v39
	v_exp_f32_e64 v103, -|v38|
	v_exp_f32_e64 v120, -|v39|
	v_min_f32_e64 v106, -v38, 0
	v_min_f32_e64 v107, -v39, 0
	v_add_f32_e32 v103, 1.0, v103
	v_add_f32_e32 v120, 1.0, v120
	v_log_f32_e32 v103, v103
	v_log_f32_e32 v120, v120
	v_sub_f32_e32 v106, v106, v103
	v_sub_f32_e32 v107, v107, v120
	v_cndmask_b32_e64 v106, 0, v106, s[48:49]
	v_cndmask_b32_e64 v107, 0, v107, s[50:51]
	v_mul_f32_e32 v40, 0x3e38aa3b, v40
	v_mul_f32_e32 v41, 0x3e38aa3b, v41
	v_exp_f32_e64 v96, -|v40|
	v_exp_f32_e64 v97, -|v41|
	v_min_f32_e64 v108, -v40, 0
	v_min_f32_e64 v109, -v41, 0
	v_add_f32_e32 v96, 1.0, v96
	v_add_f32_e32 v97, 1.0, v97
	v_log_f32_e32 v96, v96
	v_log_f32_e32 v97, v97
	v_sub_f32_e32 v108, v108, v96
	v_sub_f32_e32 v109, v109, v97
	v_cndmask_b32_e64 v108, 0, v108, s[52:53]
	v_cndmask_b32_e64 v109, 0, v109, s[54:55]
	v_mul_f32_e32 v42, 0x3e38aa3b, v42
	v_mul_f32_e32 v43, 0x3e38aa3b, v43
	v_exp_f32_e64 v103, -|v42|
	v_exp_f32_e64 v120, -|v43|
	v_min_f32_e64 v110, -v42, 0
	v_min_f32_e64 v111, -v43, 0
	v_add_f32_e32 v103, 1.0, v103
	v_add_f32_e32 v120, 1.0, v120
	v_log_f32_e32 v103, v103
	v_log_f32_e32 v120, v120
	v_sub_f32_e32 v110, v110, v103
	v_sub_f32_e32 v111, v111, v120
	v_cndmask_b32_e64 v110, 0, v110, s[56:57]
	v_cndmask_b32_e64 v111, 0, v111, s[58:59]
	v_mul_f32_e32 v44, 0x3e38aa3b, v44
	v_mul_f32_e32 v45, 0x3e38aa3b, v45
	v_exp_f32_e64 v96, -|v44|
	v_exp_f32_e64 v97, -|v45|
	v_min_f32_e64 v112, -v44, 0
	v_min_f32_e64 v113, -v45, 0
	v_add_f32_e32 v96, 1.0, v96
	v_add_f32_e32 v97, 1.0, v97
	v_log_f32_e32 v96, v96
	v_log_f32_e32 v97, v97
	v_sub_f32_e32 v112, v112, v96
	v_sub_f32_e32 v113, v113, v97
	v_cndmask_b32_e64 v112, 0, v112, s[60:61]
	v_cndmask_b32_e64 v113, 0, v113, s[62:63]
	v_mul_f32_e32 v46, 0x3e38aa3b, v46
	v_mul_f32_e32 v47, 0x3e38aa3b, v47
	v_exp_f32_e64 v103, -|v46|
	v_exp_f32_e64 v120, -|v47|
	v_min_f32_e64 v114, -v46, 0
	v_min_f32_e64 v115, -v47, 0
	v_add_f32_e32 v103, 1.0, v103
	v_add_f32_e32 v120, 1.0, v120
	v_log_f32_e32 v103, v103
	v_log_f32_e32 v120, v120
	v_sub_f32_e32 v114, v114, v103
	v_sub_f32_e32 v115, v115, v120
	v_cndmask_b32_e64 v114, 0, v114, s[64:65]
	v_cndmask_b32_e64 v115, 0, v115, s[66:67]
	v_mul_f32_e32 v48, 0x3e38aa3b, v48
	v_mul_f32_e32 v49, 0x3e38aa3b, v49
	v_exp_f32_e64 v96, -|v48|
	v_exp_f32_e64 v97, -|v49|
	v_min_f32_e64 v116, -v48, 0
	v_min_f32_e64 v117, -v49, 0
	v_add_f32_e32 v96, 1.0, v96
	v_add_f32_e32 v97, 1.0, v97
	v_log_f32_e32 v96, v96
	v_log_f32_e32 v97, v97
	v_sub_f32_e32 v116, v116, v96
	v_sub_f32_e32 v117, v117, v97
	v_cndmask_b32_e64 v116, 0, v116, s[68:69]
	v_cndmask_b32_e64 v117, 0, v117, s[70:71]
	v_mul_f32_e32 v50, 0x3e38aa3b, v50
	v_mul_f32_e32 v51, 0x3e38aa3b, v51
	v_exp_f32_e64 v103, -|v50|
	v_exp_f32_e64 v120, -|v51|
	v_min_f32_e64 v118, -v50, 0
	v_min_f32_e64 v119, -v51, 0
	v_add_f32_e32 v103, 1.0, v103
	v_add_f32_e32 v120, 1.0, v120
	v_log_f32_e32 v103, v103
; __device__ __forceinline__ unsigned cvtpk(float lo, float hi) { f32x2_t v = {lo, hi}; bf16x2_t b = __builtin_convertvector(v, bf16x2_t); return __builtin_bit_cast(unsigned, b); }
; __device__ __forceinline__ int crow(int r, int hi) { return (r & 3) + 8 * (r >> 2) + 4 * hi; }
; template <bool DRY> __device__ __forceinline__ void sb_unit(int b, int h, int qi, bf16_t* Pm, const bf16_t* VT) {
;     ...
; #pragma unroll
;         for (int g = 0; g < 4; ++g) {
;             const float s3 = lk[4 * g + 3], s2 = s3 + lk[4 * g + 2], s1 = s2 + lk[4 * g + 1];
;             inner[4 * g + 3] = 0.f; inner[4 * g + 2] = s3; inner[4 * g + 1] = s2; inner[4 * g] = s1; Tg[g] = s1 + lk[4 * g];
;             TP[g] = __shfl_xor(Tg[g], 32);
;         }
;         float run = 0.f;
; #pragma unroll
;         for (int g = 3; g >= 0; --g) { pre[g] = run + (hi == 0 ? TP[g] : 0.f); run += Tg[g] + TP[g]; }
; #pragma unroll
;         for (int r = 0; r < 16; ++r) {
;             const bool valid = !diag || (crow(r, hi) < r32);
;             const float ex = fminf(p[r] + lk[r] + R + pre[r >> 2] + inner[r], 0.f);
;             p[r] = valid ? __expf(ex) : 0.f;
;         }
;         R += run;
; #pragma unroll
;         for (int s = 0; s < 2; ++s) {
;             const u32x4 pw = (u32x4){cvtpk(p[8 * s + 0], p[8 * s + 1]), cvtpk(p[8 * s + 2], p[8 * s + 3]), cvtpk(p[8 * s + 4], p[8 * s + 5]), cvtpk(p[8 * s + 6], p[8 * s + 7])};
;             const bf16x8 pf = __builtin_bit_cast(bf16x8, pw);
;             const s16x4 l0 = cur.v[4 * s], h0 = cur.v[4 * s + 1], l1 = cur.v[4 * s + 2], h1 = cur.v[4 * s + 3];
;             const bf16x8 v0 = (bf16x8){l0[0], l0[1], l0[2], l0[3], h0[0], h0[1], h0[2], h0[3]};
;             const bf16x8 v1 = (bf16x8){l1[0], l1[1], l1[2], l1[3], h1[0], h1[1], h1[2], h1[3]};
;             o0 = __builtin_amdgcn_mfma_f32_32x32x16_bf16(v0, pf, o0, 0, 0, 0);
;             o1 = __builtin_amdgcn_mfma_f32_32x32x16_bf16(v1, pf, o1, 0, 0, 0);
;         }
;         if (__all(R < -104.f)) break;
;         cur = nxt;
;     }
	v_log_f32_e32 v120, v120
	v_sub_f32_e32 v118, v118, v103
	v_sub_f32_e32 v119, v119, v120
	v_cndmask_b32_e64 v118, 0, v118, s[72:73]
	v_cndmask_b32_e64 v119, 0, v119, s[74:75]
	v_add_f32_e32 v106, v106, v107
	v_add_f32_e32 v110, v110, v111
	v_add_f32_e32 v114, v114, v115
	v_add_f32_e32 v118, v118, v119
	v_add_f32_e32 v105, v105, v106
	v_add_f32_e32 v109, v109, v110
	v_add_f32_e32 v113, v113, v114
	v_add_f32_e32 v117, v117, v118
	v_add_f32_e32 v104, v104, v105
	v_add_f32_e32 v108, v108, v109
	v_add_f32_e32 v112, v112, v113
	v_add_f32_e32 v116, v116, v117
	v_add_f32_e32 v122, v116, v121
	v_add_f32_e32 v36, v36, v104
	v_add_f32_e32 v37, v37, v105
	v_add_f32_e32 v38, v38, v106
	v_add_f32_e32 v39, v39, v107
	v_add_f32_e32 v123, v122, v112
	v_add_f32_e32 v40, v40, v108
	v_add_f32_e32 v41, v41, v109
	v_add_f32_e32 v42, v42, v110
	v_add_f32_e32 v43, v43, v111
	v_add_f32_e32 v124, v123, v108
	v_add_f32_e32 v44, v44, v112
	v_add_f32_e32 v45, v45, v113
	v_add_f32_e32 v46, v46, v114
	v_add_f32_e32 v47, v47, v115
	v_add_f32_e32 v125, v124, v104
	v_add_f32_e32 v48, v48, v116
	v_add_f32_e32 v49, v49, v117
	v_add_f32_e32 v50, v50, v118
	v_add_f32_e32 v51, v51, v119
	v_mov_b32_e32 v126, v122
	v_cndmask_b32_e64 v130, v121, v125, s[12:13]
	v_cndmask_b32_e64 v127, v123, v122, s[12:13]
	v_cndmask_b32_e64 v128, v124, v123, s[12:13]
	v_cndmask_b32_e64 v129, v125, v124, s[12:13]
	v_permlane32_swap_b32_e32 v126, v130
	v_permlane32_swap_b32_e32 v127, v122
	v_permlane32_swap_b32_e32 v128, v123
	v_permlane32_swap_b32_e32 v129, v124
	v_add_f32_e32 v102, v125, v126
	v_add_f32_e32 v127, v127, v122
	v_add_f32_e32 v128, v128, v123
	v_add_f32_e32 v129, v129, v124
	v_add_f32_e32 v48, v48, v130
	v_add_f32_e32 v49, v49, v130
	v_add_f32_e32 v50, v50, v130
	v_add_f32_e32 v51, v51, v130
	v_add_f32_e32 v44, v44, v127
	v_add_f32_e32 v45, v45, v127
	v_add_f32_e32 v46, v46, v127
	v_add_f32_e32 v47, v47, v127
	v_add_f32_e32 v40, v40, v128
	v_add_f32_e32 v41, v41, v128
	v_add_f32_e32 v42, v42, v128
	v_add_f32_e32 v43, v43, v128
	v_add_f32_e32 v36, v36, v129
	v_add_f32_e32 v37, v37, v129
	v_add_f32_e32 v38, v38, v129
	v_add_f32_e32 v39, v39, v129
	v_exp_f32_e64 v36, v36 clamp
	v_exp_f32_e64 v37, v37 clamp
	v_exp_f32_e64 v38, v38 clamp
	v_exp_f32_e64 v39, v39 clamp
	v_exp_f32_e64 v40, v40 clamp
	v_exp_f32_e64 v41, v41 clamp
	v_exp_f32_e64 v42, v42 clamp
	v_exp_f32_e64 v43, v43 clamp
	v_exp_f32_e64 v44, v44 clamp
	v_exp_f32_e64 v45, v45 clamp
	v_exp_f32_e64 v46, v46 clamp
	v_exp_f32_e64 v47, v47 clamp
	v_exp_f32_e64 v48, v48 clamp
	v_exp_f32_e64 v49, v49 clamp
	v_exp_f32_e64 v50, v50 clamp
	v_exp_f32_e64 v51, v51 clamp
	s_nop 0
	v_cndmask_b32_e64 v36, 0, v36, s[44:45]
	v_cndmask_b32_e64 v37, 0, v37, s[46:47]
	v_cndmask_b32_e64 v38, 0, v38, s[48:49]
	v_cndmask_b32_e64 v39, 0, v39, s[50:51]
	v_cndmask_b32_e64 v40, 0, v40, s[52:53]
	v_cndmask_b32_e64 v41, 0, v41, s[54:55]
	v_cndmask_b32_e64 v42, 0, v42, s[56:57]
	v_cndmask_b32_e64 v43, 0, v43, s[58:59]
	v_cndmask_b32_e64 v44, 0, v44, s[60:61]
	v_cndmask_b32_e64 v45, 0, v45, s[62:63]
	v_cndmask_b32_e64 v46, 0, v46, s[64:65]
	v_cndmask_b32_e64 v47, 0, v47, s[66:67]
	v_cndmask_b32_e64 v48, 0, v48, s[68:69]
	v_cndmask_b32_e64 v49, 0, v49, s[70:71]
	v_cndmask_b32_e64 v50, 0, v50, s[72:73]
	v_cndmask_b32_e64 v51, 0, v51, s[74:75]
	v_cvt_pk_bf16_f32 v36, v36, v37
	v_cvt_pk_bf16_f32 v37, v38, v39
	v_cvt_pk_bf16_f32 v38, v40, v41
	v_cvt_pk_bf16_f32 v39, v42, v43
	s_mov_b32 s4, 0xc3160a50
	v_cmp_gt_f32_e32 vcc, s4, v102
	s_waitcnt lgkmcnt(0)
	v_mfma_f32_32x32x16_bf16 v[4:19], v[80:83], v[36:39], v[4:19]
	v_cvt_pk_bf16_f32 v44, v44, v45
	v_cvt_pk_bf16_f32 v45, v46, v47
	v_mfma_f32_32x32x16_bf16 v[20:35], v[76:79], v[36:39], v[20:35]
	v_cvt_pk_bf16_f32 v46, v48, v49
	v_cvt_pk_bf16_f32 v47, v50, v51
	s_cmp_eq_u32 vcc_hi, exec_hi
	s_cselect_b64 s[4:5], -1, 0
	v_cmp_eq_u32_e32 vcc, s28, v98
	s_or_b64 s[4:5], s[4:5], vcc
	s_add_i32 s28, s28, 1
	s_and_b64 s[4:5], exec, s[4:5]
	s_or_b64 s[34:35], s[4:5], s[34:35]
	v_mfma_f32_32x32x16_bf16 v[4:19], v[72:75], v[44:47], v[4:19]
	v_mfma_f32_32x32x16_bf16 v[20:35], v[68:71], v[44:47], v[20:35]
	s_andn2_b64 exec, exec, s[34:35]
	s_cbranch_execz .Lsbl_exit
.Lsbl_loop:
	s_xor_b32 s98, s98, 0x2000
	s_add_i32 m0, s98, 0
	s_nop 0
	global_load_lds_dwordx4 v[172:173], off
	s_add_i32 m0, s98, 1024
	s_nop 0
	global_load_lds_dwordx4 v[174:175], off
	s_add_i32 m0, s98, 2048
	s_nop 0
	global_load_lds_dwordx4 v[176:177], off
	s_add_i32 m0, s98, 3072
	s_nop 0
	global_load_lds_dwordx4 v[178:179], off
	s_add_i32 m0, s98, 4096
	s_nop 0
	global_load_lds_dwordx4 v[180:181], off
	s_add_i32 m0, s98, 5120
	s_nop 0
	global_load_lds_dwordx4 v[182:183], off
	s_add_i32 m0, s98, 6144
	s_nop 0
	global_load_lds_dwordx4 v[184:185], off
	s_add_i32 m0, s98, 7168
	s_nop 0
	global_load_lds_dwordx4 v[186:187], off
	v_cmp_lt_i32_e32 vcc, 0, v100
	v_add_u32_e32 v100, -1, v100
	s_nop 0
	s_cbranch_vccz .Lsb_nostep_c
	v_lshl_add_u64 v[172:173], v[172:173], 0, v[188:189]
	v_lshl_add_u64 v[174:175], v[174:175], 0, v[188:189]
	v_lshl_add_u64 v[176:177], v[176:177], 0, v[188:189]
	v_lshl_add_u64 v[178:179], v[178:179], 0, v[188:189]
	v_lshl_add_u64 v[180:181], v[180:181], 0, v[190:191]
	v_lshl_add_u64 v[182:183], v[182:183], 0, v[190:191]
	v_lshl_add_u64 v[184:185], v[184:185], 0, v[190:191]
	v_lshl_add_u64 v[186:187], v[186:187], 0, v[190:191]
; __device__ __forceinline__ void sb_load(SbFrags& F, const bf16_t* Pm, const bf16_t* VT, size_t tok0, int kv0, int h, int r32, int hi) {
;     const bf16_t* krow = Pm + (tok0 + kv0 + r32) * PW + PC_SBK + h * 64;
; #pragma unroll
;     for (int s = 0; s < 4; ++s) F.kf[s] = *(const bf16x8*)(krow + 16 * s + 8 * hi);
; #pragma unroll
;     for (int s = 0; s < 2; ++s) {
;         const bf16_t* v0p = VT + (size_t)(h * 64 + r32) * VTLD + tok0 + kv0 + 16 * s + 4 * hi; const bf16_t* v1p = v0p + (size_t)32 * VTLD;
;         F.v[4 * s + 0] = *(const s16x4*)v0p; F.v[4 * s + 1] = *(const s16x4*)(v0p + 8); F.v[4 * s + 2] = *(const s16x4*)v1p; F.v[4 * s + 3] = *(const s16x4*)(v1p + 8);
;     }
; template <bool DRY> __device__ __forceinline__ void sb_unit(int b, int h, int qi, bf16_t* Pm, const bf16_t* VT) {
;     ...
;         sb_load(nxt, Pm, VT, tok0, (kt > 0 ? kt - 1 : 0) * 32, h, r32, hi);
;         f32x16 p = {};
; #pragma unroll
;         for (int s = 0; s < 4; ++s) p = __builtin_amdgcn_mfma_f32_32x32x16_bf16(cur.kf[s], qf[s], p, 0, 0, 0);
.Lsb_nostep_c:
	s_xor_b32 s99, s98, 0x2000
	v_add_u32_e32 v210, s99, v192
	v_add_u32_e32 v211, s99, v193
	v_add_u32_e32 v212, s99, v194
	v_add_u32_e32 v213, s99, v195
	v_add_u32_e32 v214, s99, v196
	v_add_u32_e32 v215, s99, v197
	v_add_u32_e32 v216, s99, v198
	v_add_u32_e32 v217, s99, v199
	s_waitcnt vmcnt(8)
	ds_read_b128 v[136:139], v210
	ds_read_b128 v[112:115], v211
	ds_read_b128 v[108:111], v212
	ds_read_b128 v[104:107], v213
	ds_read_b64 v[80:81], v214 offset:4096
	ds_read_b64 v[82:83], v215 offset:4096
	ds_read_b64 v[72:73], v216 offset:4096
	ds_read_b64 v[74:75], v217 offset:4096
	ds_read_b64 v[76:77], v214 offset:6144
	ds_read_b64 v[78:79], v215 offset:6144
	ds_read_b64 v[68:69], v216 offset:6144
	ds_read_b64 v[70:71], v217 offset:6144
	s_waitcnt lgkmcnt(8)
; __device__ __forceinline__ int crow(int r, int hi) { return (r & 3) + 8 * (r >> 2) + 4 * hi; }
; template <bool DRY> __device__ __forceinline__ void sb_unit(int b, int h, int qi, bf16_t* Pm, const bf16_t* VT) {
;     ...
;         for (int s = 0; s < 4; ++s) p = __builtin_amdgcn_mfma_f32_32x32x16_bf16(cur.kf[s], qf[s], p, 0, 0, 0);
;         const bool diag = (kt == qi);
;         float lk[16], inner[16], Tg[4], TP[4], pre[4];
; #pragma unroll
;         for (int r = 0; r < 16; ++r) {
;             const float z = p[r] * 0.125f; p[r] = z;
;             const float e = __expf(-fabsf(z)); const float sp = fmaxf(z, 0.f) + __logf(1.f + e);
;             const bool valid = !diag || (crow(r, hi) < r32);
;             lk[r] = valid ? -sp : 0.f;
;         }
; #pragma unroll
;         for (int g = 0; g < 4; ++g) {
;             const float s3 = lk[4 * g + 3], s2 = s3 + lk[4 * g + 2], s1 = s2 + lk[4 * g + 1];
;             inner[4 * g + 3] = 0.f; inner[4 * g + 2] = s3; inner[4 * g + 1] = s2; inner[4 * g] = s1; Tg[g] = s1 + lk[4 * g];
;             TP[g] = __shfl_xor(Tg[g], 32);
;         }
;         float run = 0.f;
; #pragma unroll
;         for (int g = 3; g >= 0; --g) { pre[g] = run + (hi == 0 ? TP[g] : 0.f); run += Tg[g] + TP[g]; }
; #pragma unroll
;         for (int r = 0; r < 16; ++r) {
;             const bool valid = !diag || (crow(r, hi) < r32);
;             const float ex = fminf(p[r] + lk[r] + R + pre[r >> 2] + inner[r], 0.f);
;             p[r] = valid ? __expf(ex) : 0.f;
;         }
;         R += run;
; #pragma unroll
;         for (int s = 0; s < 2; ++s) {
;             const u32x4 pw = (u32x4){cvtpk(p[8 * s + 0], p[8 * s + 1]), cvtpk(p[8 * s + 2], p[8 * s + 3]), cvtpk(p[8 * s + 4], p[8 * s + 5]), cvtpk(p[8 * s + 6], p[8 * s + 7])};
;             const bf16x8 pf = __builtin_bit_cast(bf16x8, pw);
;             const s16x4 l0 = cur.v[4 * s], h0 = cur.v[4 * s + 1], l1 = cur.v[4 * s + 2], h1 = cur.v[4 * s + 3];
;             const bf16x8 v0 = (bf16x8){l0[0], l0[1], l0[2], l0[3], h0[0], h0[1], h0[2], h0[3]};
;             const bf16x8 v1 = (bf16x8){l1[0], l1[1], l1[2], l1[3], h1[0], h1[1], h1[2], h1[3]};
;             o0 = __builtin_amdgcn_mfma_f32_32x32x16_bf16(v0, pf, o0, 0, 0, 0);
;             o1 = __builtin_amdgcn_mfma_f32_32x32x16_bf16(v1, pf, o1, 0, 0, 0);
;         }
;         if (__all(R < -104.f)) break;
;         cur = nxt;
;     }
	v_mfma_f32_32x32x16_bf16 v[36:51], v[136:139], v[52:55], 0
	v_mfma_f32_32x32x16_bf16 v[36:51], v[112:115], v[56:59], v[36:51]
	v_mfma_f32_32x32x16_bf16 v[36:51], v[108:111], v[60:63], v[36:51]
	v_mfma_f32_32x32x16_bf16 v[36:51], v[104:107], v[64:67], v[36:51]
	s_nop 11
	v_mul_f32_e32 v36, 0x3e38aa3b, v36
	v_mul_f32_e32 v37, 0x3e38aa3b, v37
	v_exp_f32_e64 v96, -|v36|
	v_exp_f32_e64 v97, -|v37|
	v_min_f32_e64 v104, -v36, 0
	v_min_f32_e64 v105, -v37, 0
	v_add_f32_e32 v96, 1.0, v96
	v_add_f32_e32 v97, 1.0, v97
	v_log_f32_e32 v96, v96
	v_log_f32_e32 v97, v97
	v_cndmask_b32_e64 v121, v102, 0, s[12:13]
	v_sub_f32_e32 v104, v104, v96
	v_sub_f32_e32 v105, v105, v97
	v_mul_f32_e32 v38, 0x3e38aa3b, v38
	v_mul_f32_e32 v39, 0x3e38aa3b, v39
	v_exp_f32_e64 v103, -|v38|
	v_exp_f32_e64 v120, -|v39|
	v_min_f32_e64 v106, -v38, 0
	v_min_f32_e64 v107, -v39, 0
	v_add_f32_e32 v103, 1.0, v103
	v_add_f32_e32 v120, 1.0, v120
	v_log_f32_e32 v103, v103
	v_log_f32_e32 v120, v120
	v_sub_f32_e32 v106, v106, v103
	v_sub_f32_e32 v107, v107, v120
	v_mul_f32_e32 v40, 0x3e38aa3b, v40
	v_mul_f32_e32 v41, 0x3e38aa3b, v41
	v_exp_f32_e64 v96, -|v40|
	v_exp_f32_e64 v97, -|v41|
	v_min_f32_e64 v108, -v40, 0
	v_min_f32_e64 v109, -v41, 0
	v_add_f32_e32 v96, 1.0, v96
	v_add_f32_e32 v97, 1.0, v97
	v_log_f32_e32 v96, v96
	v_log_f32_e32 v97, v97
	v_sub_f32_e32 v108, v108, v96
	v_sub_f32_e32 v109, v109, v97
	v_mul_f32_e32 v42, 0x3e38aa3b, v42
	v_mul_f32_e32 v43, 0x3e38aa3b, v43
	v_exp_f32_e64 v103, -|v42|
	v_exp_f32_e64 v120, -|v43|
	v_min_f32_e64 v110, -v42, 0
	v_min_f32_e64 v111, -v43, 0
	v_add_f32_e32 v103, 1.0, v103
	v_add_f32_e32 v120, 1.0, v120
	v_log_f32_e32 v103, v103
	v_log_f32_e32 v120, v120
	v_sub_f32_e32 v110, v110, v103
	v_sub_f32_e32 v111, v111, v120
	v_mul_f32_e32 v44, 0x3e38aa3b, v44
	v_mul_f32_e32 v45, 0x3e38aa3b, v45
	v_exp_f32_e64 v96, -|v44|
	v_exp_f32_e64 v97, -|v45|
	v_min_f32_e64 v112, -v44, 0
	v_min_f32_e64 v113, -v45, 0
	v_add_f32_e32 v96, 1.0, v96
	v_add_f32_e32 v97, 1.0, v97
	v_log_f32_e32 v96, v96
	v_log_f32_e32 v97, v97
	v_sub_f32_e32 v112, v112, v96
	v_sub_f32_e32 v113, v113, v97
	v_mul_f32_e32 v46, 0x3e38aa3b, v46
	v_mul_f32_e32 v47, 0x3e38aa3b, v47
	v_exp_f32_e64 v103, -|v46|
	v_exp_f32_e64 v120, -|v47|
	v_min_f32_e64 v114, -v46, 0
	v_min_f32_e64 v115, -v47, 0
	v_add_f32_e32 v103, 1.0, v103
	v_add_f32_e32 v120, 1.0, v120
	v_log_f32_e32 v103, v103
	v_log_f32_e32 v120, v120
	v_sub_f32_e32 v114, v114, v103
	v_sub_f32_e32 v115, v115, v120
	v_mul_f32_e32 v48, 0x3e38aa3b, v48
	v_mul_f32_e32 v49, 0x3e38aa3b, v49
	v_exp_f32_e64 v96, -|v48|
	v_exp_f32_e64 v97, -|v49|
	v_min_f32_e64 v116, -v48, 0
	v_min_f32_e64 v117, -v49, 0
	v_add_f32_e32 v96, 1.0, v96
	v_add_f32_e32 v97, 1.0, v97
	v_log_f32_e32 v96, v96
	v_log_f32_e32 v97, v97
	v_sub_f32_e32 v116, v116, v96
	v_sub_f32_e32 v117, v117, v97
	v_mul_f32_e32 v50, 0x3e38aa3b, v50
	v_mul_f32_e32 v51, 0x3e38aa3b, v51
	v_exp_f32_e64 v103, -|v50|
	v_exp_f32_e64 v120, -|v51|
	v_min_f32_e64 v118, -v50, 0
	v_min_f32_e64 v119, -v51, 0
	v_add_f32_e32 v103, 1.0, v103
	v_add_f32_e32 v120, 1.0, v120
	v_log_f32_e32 v103, v103
	v_log_f32_e32 v120, v120
	v_sub_f32_e32 v118, v118, v103
	v_sub_f32_e32 v119, v119, v120
	v_add_f32_e32 v106, v106, v107
	v_add_f32_e32 v110, v110, v111
	v_add_f32_e32 v114, v114, v115
	v_add_f32_e32 v118, v118, v119
	v_add_f32_e32 v105, v105, v106
	v_add_f32_e32 v109, v109, v110
	v_add_f32_e32 v113, v113, v114
	v_add_f32_e32 v117, v117, v118
	v_add_f32_e32 v104, v104, v105
	v_add_f32_e32 v108, v108, v109
	v_add_f32_e32 v112, v112, v113
	v_add_f32_e32 v116, v116, v117
	v_add_f32_e32 v122, v116, v121
	v_add_f32_e32 v36, v36, v104
	v_add_f32_e32 v37, v37, v105
	v_add_f32_e32 v38, v38, v106
	v_add_f32_e32 v39, v39, v107
	v_add_f32_e32 v123, v122, v112
	v_add_f32_e32 v40, v40, v108
	v_add_f32_e32 v41, v41, v109
	v_add_f32_e32 v42, v42, v110
	v_add_f32_e32 v43, v43, v111
	v_add_f32_e32 v124, v123, v108
	v_add_f32_e32 v44, v44, v112
	v_add_f32_e32 v45, v45, v113
	v_add_f32_e32 v46, v46, v114
	v_add_f32_e32 v47, v47, v115
	v_add_f32_e32 v125, v124, v104
	v_add_f32_e32 v48, v48, v116
	v_add_f32_e32 v49, v49, v117
	v_add_f32_e32 v50, v50, v118
	v_add_f32_e32 v51, v51, v119
	v_mov_b32_e32 v126, v122
	v_cndmask_b32_e64 v130, v121, v125, s[12:13]
	v_cndmask_b32_e64 v127, v123, v122, s[12:13]
	v_cndmask_b32_e64 v128, v124, v123, s[12:13]
	v_cndmask_b32_e64 v129, v125, v124, s[12:13]
	v_permlane32_swap_b32_e32 v126, v130
	v_permlane32_swap_b32_e32 v127, v122
	v_permlane32_swap_b32_e32 v128, v123
	v_permlane32_swap_b32_e32 v129, v124
	v_add_f32_e32 v102, v125, v126
	v_add_f32_e32 v127, v127, v122
	v_add_f32_e32 v128, v128, v123
	v_add_f32_e32 v129, v129, v124
	v_add_f32_e32 v48, v48, v130
	v_add_f32_e32 v49, v49, v130
	v_add_f32_e32 v50, v50, v130
	v_add_f32_e32 v51, v51, v130
	v_add_f32_e32 v44, v44, v127
	v_add_f32_e32 v45, v45, v127
	v_add_f32_e32 v46, v46, v127
	v_add_f32_e32 v47, v47, v127
	v_add_f32_e32 v40, v40, v128
	v_add_f32_e32 v41, v41, v128
	v_add_f32_e32 v42, v42, v128
	v_add_f32_e32 v43, v43, v128
	v_add_f32_e32 v36, v36, v129
	v_add_f32_e32 v37, v37, v129
	v_add_f32_e32 v38, v38, v129
	v_add_f32_e32 v39, v39, v129
	v_exp_f32_e64 v36, v36 clamp
	v_exp_f32_e64 v37, v37 clamp
	v_exp_f32_e64 v38, v38 clamp
	v_exp_f32_e64 v39, v39 clamp
	v_exp_f32_e64 v40, v40 clamp
	v_exp_f32_e64 v41, v41 clamp
	v_exp_f32_e64 v42, v42 clamp
	v_exp_f32_e64 v43, v43 clamp
	v_exp_f32_e64 v44, v44 clamp
	v_exp_f32_e64 v45, v45 clamp
	v_exp_f32_e64 v46, v46 clamp
	v_exp_f32_e64 v47, v47 clamp
	v_exp_f32_e64 v48, v48 clamp
	v_exp_f32_e64 v49, v49 clamp
	v_exp_f32_e64 v50, v50 clamp
	v_exp_f32_e64 v51, v51 clamp
	s_nop 0
	v_cvt_pk_bf16_f32 v36, v36, v37
	v_cvt_pk_bf16_f32 v37, v38, v39
	v_cvt_pk_bf16_f32 v38, v40, v41
	v_cvt_pk_bf16_f32 v39, v42, v43
	s_mov_b32 s4, 0xc3160a50
	v_cmp_gt_f32_e32 vcc, s4, v102
	s_waitcnt lgkmcnt(0)
	v_mfma_f32_32x32x16_bf16 v[4:19], v[80:83], v[36:39], v[4:19]
	v_cvt_pk_bf16_f32 v44, v44, v45
	v_cvt_pk_bf16_f32 v45, v46, v47
	v_mfma_f32_32x32x16_bf16 v[20:35], v[76:79], v[36:39], v[20:35]
	v_cvt_pk_bf16_f32 v46, v48, v49
	v_cvt_pk_bf16_f32 v47, v50, v51
	s_cmp_eq_u32 vcc_hi, exec_hi
	s_cselect_b64 s[4:5], -1, 0
	v_cmp_eq_u32_e32 vcc, s28, v98
	s_or_b64 s[4:5], s[4:5], vcc
	s_add_i32 s28, s28, 1
	s_and_b64 s[4:5], exec, s[4:5]
	s_or_b64 s[34:35], s[4:5], s[34:35]
	v_mfma_f32_32x32x16_bf16 v[4:19], v[72:75], v[44:47], v[4:19]
	v_mfma_f32_32x32x16_bf16 v[20:35], v[68:71], v[44:47], v[20:35]
	s_andn2_b64 exec, exec, s[34:35]
	s_cbranch_execnz .Lsbl_loop
